# weight conversion in phases 2 and 9: gain vector staged in LDS, tile-body vector-memory wait removed
# speedup vs baseline: 1.0148x; 1.0025x over previous
.LBB0_333:
	s_lshr_b32 s20, s42, 6
	v_cvt_f32_ubyte0_e32 v0, s20
	v_rcp_iflag_f32_e32 v0, v0
	s_sub_i32 s23, 0, s20
	s_abs_i32 s22, s46
	s_ashr_i32 s21, s46, 31
	v_mul_f32_e32 v0, 0x4f7ffffe, v0
	v_cvt_u32_f32_e32 v0, v0
	v_ashrrev_i32_e32 v21, 4, v142
	v_ashrrev_i32_e32 v25, 3, v142
	v_lshl_add_u32 v5, v25, 2, 0
	v_readfirstlane_b32 s28, v0
	s_mul_i32 s23, s23, s28
	s_mul_hi_u32 s23, s28, s23
	s_add_i32 s28, s28, s23
	s_mul_hi_u32 s23, s22, s28
	s_mul_i32 s28, s23, s20
	s_sub_i32 s22, s22, s28
	s_add_i32 s29, s23, 1
	s_sub_i32 s28, s22, s20
	s_cmp_ge_u32 s22, s20
	s_cselect_b32 s23, s29, s23
	s_cselect_b32 s22, s28, s22
	s_add_i32 s28, s23, 1
	s_cmp_ge_u32 s22, s20
	s_cselect_b32 s22, s28, s23
	s_xor_b32 s22, s22, s21
	s_sub_i32 s21, s22, s21
	s_mul_i32 s20, s21, s20
	v_lshl_add_u32 v0, s21, 6, v21
	s_sub_i32 s22, s46, s20
	v_mad_i64_i32 v[2:3], s[20:21], v0, s42, 0
	v_lshl_add_u64 v[2:3], v[2:3], 2, s[2:3]
	s_lshl_b32 s2, s22, 6
	v_lshlrev_b32_e32 v0, 2, v142
	s_ashr_i32 s3, s2, 31
	v_and_b32_e32 v4, 60, v0
	v_lshl_add_u64 v[2:3], s[2:3], 2, v[2:3]
	v_lshlrev_b32_e32 v0, 2, v4
	v_lshl_add_u64 v[2:3], v[2:3], 0, v[0:1]
	s_lshl_b32 s96, s42, 7
	v_lshl_add_u64 v[6:7], v[2:3], 0, s[96:97]
	global_load_dwordx4 v[16:19], v[2:3], off nt
	global_load_dwordx4 v[12:15], v[6:7], off nt
	s_movk_i32 s2, 0x104
	v_mul_lo_u32 v2, v21, s2
	v_add3_u32 v24, 0, v2, v0
	v_lshlrev_b32_e32 v0, 3, v142
	v_and_b32_e32 v20, 56, v0
	v_mul_u32_u24_e32 v6, 0x104, v20
	v_mov_b32_e32 v2, v1
	v_mov_b32_e32 v3, v1
	v_mov_b32_e32 v0, v1
	v_lshlrev_b32_e32 v22, 2, v4
	v_add_u32_e32 v26, v5, v6
	v_mov_b64_e32 v[6:7], v[2:3]
	v_mov_b64_e32 v[10:11], v[2:3]
	v_readlane_b32 s40, v253, 60
	v_readlane_b32 s41, v250, 37
	v_mov_b64_e32 v[4:5], v[0:1]
	v_mov_b64_e32 v[8:9], v[0:1]
	v_readlane_b32 s68, v250, 42
	s_cmp_eq_u64 s[36:37], 0
	s_cbranch_scc1 .Lgkp_0
	v_lshlrev_b32_e32 v44, 3, v160
	global_load_dwordx2 v[36:37], v44, s[36:37]
	v_add_u32_e32 v45, 0x8000, v44
	s_waitcnt vmcnt(0)
	s_barrier
	ds_write_b64 v45, v[36:37]
.Lgkp_0:
	s_waitcnt vmcnt(0)
	s_branch .LBB0_338

.LBB0_349:
	s_ashr_i32 s21, s42, 6
	s_abs_i32 s22, s21
	v_cvt_f32_u32_e32 v0, s22
	s_sub_i32 s43, 0, s22
	s_abs_i32 s23, s46
	s_xor_b32 s42, s46, s21
	v_rcp_iflag_f32_e32 v0, v0
	s_ashr_i32 s42, s42, 31
	ds_write2_b32 v24, v16, v17 offset1:1
	ds_write2_b32 v24, v18, v19 offset0:2 offset1:3
	v_add_u32_e32 v2, 0x2080, v24
	v_mul_f32_e32 v0, 0x4f7ffffe, v0
	v_cvt_u32_f32_e32 v0, v0
	ds_write2_b32 v2, v12, v13 offset1:1
	v_readfirstlane_b32 s47, v0
	s_mul_i32 s43, s43, s47
	s_mul_hi_u32 s43, s47, s43
	s_add_i32 s47, s47, s43
	s_mul_hi_u32 s43, s23, s47
	s_mul_i32 s47, s43, s22
	s_sub_i32 s23, s23, s47
	s_add_i32 s65, s43, 1
	s_sub_i32 s47, s23, s22
	s_cmp_ge_u32 s23, s22
	s_cselect_b32 s43, s65, s43
	s_cselect_b32 s23, s47, s23
	s_add_i32 s47, s43, 1
	v_add_u32_e32 v0, 0x2088, v24
	s_cmp_ge_u32 s23, s22
	ds_write2_b32 v0, v14, v15 offset1:1
	v_add_u32_e32 v0, 0x400, v26
	s_cselect_b32 s22, s47, s43
	s_waitcnt lgkmcnt(0)
	s_barrier
	ds_read2_b32 v[12:13], v26 offset1:65
	ds_read2_b32 v[14:15], v26 offset0:130 offset1:195
	ds_read2_b32 v[16:17], v0 offset0:4 offset1:69
	ds_read2_b32 v[2:3], v0 offset0:134 offset1:199
	s_xor_b32 s22, s22, s42
	s_sub_i32 s22, s22, s42
	s_lshl_b32 s42, s22, 6
	s_cmp_eq_u64 s[36:37], 0
	s_cbranch_scc1 .LBB0_351
	s_lshl_b32 s43, s42, 2
	s_add_i32 s43, s43, 0x8000
	v_lshl_add_u32 v0, v20, 2, s43
	ds_read_b128 v[28:31], v0
	ds_read_b128 v[32:35], v0 offset:16
	s_waitcnt lgkmcnt(1)
	v_pk_mul_f32 v[14:15], v[14:15], v[30:31]
	v_pk_mul_f32 v[12:13], v[12:13], v[28:29]
	s_waitcnt lgkmcnt(0)
	v_pk_mul_f32 v[2:3], v[2:3], v[34:35]
	v_pk_mul_f32 v[16:17], v[16:17], v[32:33]

.LBB0_382:
	s_lshr_b32 s22, s42, 6
	v_cvt_f32_ubyte0_e32 v0, s22
	v_rcp_iflag_f32_e32 v0, v0
	s_sub_i32 s29, 0, s22
	s_abs_i32 s28, s45
	s_ashr_i32 s23, s45, 31
	v_mul_f32_e32 v0, 0x4f7ffffe, v0
	v_cvt_u32_f32_e32 v0, v0
	v_ashrrev_i32_e32 v21, 4, v142
	v_ashrrev_i32_e32 v25, 3, v142
	v_lshl_add_u32 v5, v25, 2, 0
	v_readfirstlane_b32 s30, v0
	s_mul_i32 s29, s29, s30
	s_mul_hi_u32 s29, s30, s29
	s_add_i32 s30, s30, s29
	s_mul_hi_u32 s29, s28, s30
	s_mul_i32 s30, s29, s22
	s_sub_i32 s28, s28, s30
	s_add_i32 s31, s29, 1
	s_sub_i32 s30, s28, s22
	s_cmp_ge_u32 s28, s22
	s_cselect_b32 s29, s31, s29
	s_cselect_b32 s28, s30, s28
	s_add_i32 s30, s29, 1
	s_cmp_ge_u32 s28, s22
	s_cselect_b32 s28, s30, s29
	s_xor_b32 s28, s28, s23
	s_sub_i32 s23, s28, s23
	s_mul_i32 s22, s23, s22
	v_lshl_add_u32 v0, s23, 6, v21
	s_sub_i32 s28, s45, s22
	v_mad_i64_i32 v[2:3], s[22:23], v0, s42, 0
	v_lshl_add_u64 v[2:3], v[2:3], 2, s[20:21]
	s_lshl_b32 s20, s28, 6
	v_lshlrev_b32_e32 v0, 2, v142
	s_ashr_i32 s21, s20, 31
	v_and_b32_e32 v4, 60, v0
	v_lshl_add_u64 v[2:3], s[20:21], 2, v[2:3]
	v_lshlrev_b32_e32 v0, 2, v4
	v_lshl_add_u64 v[2:3], v[2:3], 0, v[0:1]
	s_lshl_b32 s96, s42, 7
	v_lshl_add_u64 v[6:7], v[2:3], 0, s[96:97]
	global_load_dwordx4 v[16:19], v[2:3], off nt
	global_load_dwordx4 v[12:15], v[6:7], off nt
	s_movk_i32 s20, 0x104
	v_mul_lo_u32 v2, v21, s20
	v_add3_u32 v24, 0, v2, v0
	v_lshlrev_b32_e32 v0, 3, v142
	v_and_b32_e32 v20, 56, v0
	v_mul_u32_u24_e32 v6, 0x104, v20
	v_mov_b32_e32 v2, v1
	v_mov_b32_e32 v3, v1
	v_mov_b32_e32 v0, v1
	v_lshlrev_b32_e32 v22, 2, v4
	v_add_u32_e32 v26, v5, v6
	v_mov_b64_e32 v[6:7], v[2:3]
	v_mov_b64_e32 v[10:11], v[2:3]
	v_readlane_b32 s33, v253, 61
	v_readlane_b32 s35, v250, 45
	v_mov_b64_e32 v[4:5], v[0:1]
	v_mov_b64_e32 v[8:9], v[0:1]
	s_cmp_eq_u64 s[2:3], 0
	s_cbranch_scc1 .Lgkp_1
	v_lshlrev_b32_e32 v44, 3, v160
	global_load_dwordx2 v[36:37], v44, s[2:3]
	v_add_u32_e32 v45, 0x8000, v44
	s_waitcnt vmcnt(0)
	s_barrier
	ds_write_b64 v45, v[36:37]

.LBB0_402:
	s_ashr_i32 s22, s42, 6
	s_abs_i32 s23, s22
	v_cvt_f32_u32_e32 v0, s23
	s_sub_i32 s43, 0, s23
	s_abs_i32 s29, s45
	s_xor_b32 s42, s45, s22
	v_rcp_iflag_f32_e32 v0, v0
	s_ashr_i32 s42, s42, 31
	ds_write2_b32 v24, v16, v17 offset1:1
	ds_write2_b32 v24, v18, v19 offset0:2 offset1:3
	v_add_u32_e32 v2, 0x2080, v24
	v_mul_f32_e32 v0, 0x4f7ffffe, v0
	v_cvt_u32_f32_e32 v0, v0
	ds_write2_b32 v2, v12, v13 offset1:1
	v_readfirstlane_b32 s46, v0
	s_mul_i32 s43, s43, s46
	s_mul_hi_u32 s43, s46, s43
	s_add_i32 s46, s46, s43
	s_mul_hi_u32 s43, s29, s46
	s_mul_i32 s46, s43, s23
	s_sub_i32 s29, s29, s46
	s_add_i32 s47, s43, 1
	s_sub_i32 s46, s29, s23
	s_cmp_ge_u32 s29, s23
	s_cselect_b32 s43, s47, s43
	s_cselect_b32 s29, s46, s29
	s_add_i32 s46, s43, 1
	v_add_u32_e32 v0, 0x2088, v24
	s_cmp_ge_u32 s29, s23
	ds_write2_b32 v0, v14, v15 offset1:1
	v_add_u32_e32 v0, 0x400, v26
	s_cselect_b32 s23, s46, s43
	s_waitcnt lgkmcnt(0)
	s_barrier
	ds_read2_b32 v[12:13], v26 offset1:65
	ds_read2_b32 v[14:15], v26 offset0:130 offset1:195
	ds_read2_b32 v[16:17], v0 offset0:4 offset1:69
	ds_read2_b32 v[2:3], v0 offset0:134 offset1:199
	s_xor_b32 s23, s23, s42
	s_sub_i32 s23, s23, s42
	s_lshl_b32 s42, s23, 6
	s_cmp_eq_u64 s[2:3], 0
	s_cbranch_scc1 .LBB0_404
	s_lshl_b32 s43, s42, 2
	s_add_i32 s43, s43, 0x8000
	v_lshl_add_u32 v0, v20, 2, s43
	ds_read_b128 v[28:31], v0
	ds_read_b128 v[32:35], v0 offset:16
	s_waitcnt lgkmcnt(1)
	v_pk_mul_f32 v[14:15], v[14:15], v[30:31]
	v_pk_mul_f32 v[12:13], v[12:13], v[28:29]
	s_waitcnt lgkmcnt(0)
	v_pk_mul_f32 v[2:3], v[2:3], v[34:35]
	v_pk_mul_f32 v[16:17], v[16:17], v[32:33]
